# attnA: barrier arrival moved up to before PV MFMA 8 (all V^T fragment reads issued by then)
# baseline (speedup 1.0000x reference)
.LBB0_1369:
	s_or_b32 s82, s34, 1
	s_lshl_b64 s[4:5], s[82:83], 7
	s_add_u32 s4, s8, s4
	s_addc_u32 s5, s9, s5
	s_add_u32 m0, s38, 0x8000
	s_nop 0
	global_load_lds_dwordx4 v198, s[4:5]
	s_add_u32 m0, s38, 0x9000
	s_nop 0
	global_load_lds_dwordx4 v199, s[4:5]
	s_add_u32 m0, s38, 0xa000
	s_nop 0
	global_load_lds_dwordx4 v200, s[4:5]
	s_add_u32 m0, s38, 0xb000
	s_nop 0
	global_load_lds_dwordx4 v201, s[4:5]
	v_cmp_lt_i32_e64 s[4:5], s34, v226
	s_and_saveexec_b64 s[22:23], s[4:5]
	s_cbranch_execz .LBB0_1371
	ds_read_b128 v[2:5], v222 offset:24576
	ds_read_b128 v[6:9], v222 offset:28672
	ds_read_b128 v[10:13], v223 offset:24576
	ds_read_b128 v[244:247], v223 offset:28672
	s_waitcnt lgkmcnt(3)
	v_mfma_f32_32x32x16_bf16 v[128:143], v[2:5], v[160:163], v[16:31]
	v_exp_f32_e32 v32, v32
	v_exp_f32_e32 v33, v33
	ds_read_b128 v[2:5], v224 offset:24576
	s_waitcnt lgkmcnt(3)
	v_mfma_f32_32x32x16_bf16 v[144:159], v[6:9], v[160:163], v[16:31]
	v_exp_f32_e32 v34, v34
	v_exp_f32_e32 v35, v35
	ds_read_b128 v[6:9], v224 offset:28672
	s_waitcnt lgkmcnt(3)
	v_mfma_f32_32x32x16_bf16 v[128:143], v[10:13], v[164:167], v[128:143]
	v_exp_f32_e32 v36, v36
	v_exp_f32_e32 v37, v37
	v_add_f32_e32 v0, 0, v32
	ds_read_b128 v[10:13], v225 offset:24576
	s_waitcnt lgkmcnt(3)
	v_mfma_f32_32x32x16_bf16 v[144:159], v[244:247], v[164:167], v[144:159]
	v_exp_f32_e32 v38, v38
	v_exp_f32_e32 v39, v39
	v_add_f32_e32 v0, v33, v0
	ds_read_b128 v[244:247], v225 offset:28672
	s_waitcnt lgkmcnt(3)
	v_mfma_f32_32x32x16_bf16 v[128:143], v[2:5], v[168:171], v[128:143]
	v_cvt_pk_bf16_f32 v208, v32, v33
	v_add_f32_e32 v0, v34, v0
	v_add_f32_e32 v0, v35, v0
	s_waitcnt lgkmcnt(2)
	v_mfma_f32_32x32x16_bf16 v[144:159], v[6:9], v[168:171], v[144:159]
	v_cvt_pk_bf16_f32 v209, v34, v35
	v_add_f32_e32 v0, v36, v0
	v_add_f32_e32 v0, v37, v0
	s_waitcnt lgkmcnt(1)
	v_mfma_f32_32x32x16_bf16 v[128:143], v[10:13], v[172:175], v[128:143]
	v_cvt_pk_bf16_f32 v210, v36, v37
	v_add_f32_e32 v0, v38, v0
	s_waitcnt lgkmcnt(0)
	v_mfma_f32_32x32x16_bf16 v[144:159], v[244:247], v[172:175], v[144:159]
	v_cvt_pk_bf16_f32 v211, v38, v39
	v_add_f32_e32 v0, v39, v0
	s_or_b64 exec, exec, s[22:23]
	v_cmp_le_i32_e32 vcc, s34, v226
	s_and_saveexec_b64 s[22:23], vcc
	ds_read_b64 v[6:7], v228 offset:8192
	ds_read_b64 v[8:9], v229 offset:8192
	ds_read_b64 v[10:11], v230 offset:20480
	ds_read_b64 v[12:13], v231 offset:20480
	ds_read_b64 v[244:245], v230 offset:12288
	ds_read_b64 v[246:247], v231 offset:12288
	ds_read_b64 v[32:33], v230 offset:16384
	ds_read_b64 v[34:35], v231 offset:16384
	ds_read_b64 v[36:37], v232 offset:8192
	ds_read_b64 v[38:39], v233 offset:8192
	s_waitcnt lgkmcnt(8)
	v_mfma_f32_32x32x16_bf16 v[112:127], v[6:9], v[208:211], v[112:127]
	ds_read_b64 v[6:7], v234 offset:20480
	ds_read_b64 v[8:9], v235 offset:20480
	v_exp_f32_e32 v40, v40
	v_exp_f32_e32 v41, v41
	s_waitcnt lgkmcnt(8)
	v_mfma_f32_32x32x16_bf16 v[64:79], v[10:13], v[208:211], v[64:79]
	ds_read_b64 v[10:11], v234 offset:12288
	ds_read_b64 v[12:13], v235 offset:12288
	v_exp_f32_e32 v42, v42
	v_exp_f32_e32 v43, v43
	v_add_f32_e32 v0, v40, v0
	v_add_f32_e32 v0, v41, v0
	s_waitcnt lgkmcnt(8)
	v_mfma_f32_32x32x16_bf16 v[96:111], v[244:247], v[208:211], v[96:111]
	ds_read_b64 v[244:245], v234 offset:16384
	ds_read_b64 v[246:247], v235 offset:16384
	v_exp_f32_e32 v44, v44
	v_exp_f32_e32 v45, v45
	v_add_f32_e32 v0, v42, v0
	v_add_f32_e32 v0, v43, v0
	s_waitcnt lgkmcnt(8)
	v_mfma_f32_32x32x16_bf16 v[80:95], v[32:35], v[208:211], v[80:95]
	ds_read_b64 v[32:33], v236 offset:8192
	ds_read_b64 v[34:35], v237 offset:8192
	v_exp_f32_e32 v46, v46
	v_exp_f32_e32 v47, v47
	v_add_f32_e32 v0, v44, v0
	v_add_f32_e32 v0, v45, v0
	v_add_f32_e32 v0, v46, v0
	v_add_f32_e32 v0, v47, v0
	v_cvt_pk_bf16_f32 v2, v40, v41
	v_cvt_pk_bf16_f32 v3, v42, v43
	v_cvt_pk_bf16_f32 v4, v44, v45
	v_cvt_pk_bf16_f32 v5, v46, v47
	s_nop 1
	ds_read_b64 v[40:41], v238 offset:20480
	ds_read_b64 v[42:43], v239 offset:20480
	ds_read_b64 v[44:45], v238 offset:12288
	ds_read_b64 v[46:47], v239 offset:12288
	s_waitcnt lgkmcnt(12)
	v_mfma_f32_32x32x16_bf16 v[112:127], v[36:39], v[2:5], v[112:127]
	ds_read_b64 v[36:37], v238 offset:16384
	ds_read_b64 v[38:39], v239 offset:16384
	v_exp_f32_e32 v48, v48
	v_exp_f32_e32 v49, v49
	s_waitcnt lgkmcnt(12)
	v_mfma_f32_32x32x16_bf16 v[64:79], v[6:9], v[2:5], v[64:79]
	ds_read_b64 v[6:7], v240 offset:8192
	ds_read_b64 v[8:9], v241 offset:8192
	v_exp_f32_e32 v50, v50
	v_exp_f32_e32 v51, v51
	v_add_f32_e32 v0, v48, v0
	v_add_f32_e32 v0, v49, v0
	s_waitcnt lgkmcnt(12)
	v_mfma_f32_32x32x16_bf16 v[96:111], v[10:13], v[2:5], v[96:111]
	ds_read_b64 v[10:11], v242 offset:12288
	ds_read_b64 v[12:13], v243 offset:12288
	v_exp_f32_e32 v52, v52
	v_exp_f32_e32 v53, v53
	v_add_f32_e32 v0, v50, v0
	v_add_f32_e32 v0, v51, v0
	s_waitcnt lgkmcnt(12)
	v_mfma_f32_32x32x16_bf16 v[80:95], v[244:247], v[2:5], v[80:95]
	ds_read_b64 v[244:245], v242 offset:16384
	ds_read_b64 v[246:247], v243 offset:16384
	v_exp_f32_e32 v54, v54
	v_exp_f32_e32 v55, v55
	v_add_f32_e32 v0, v52, v0
	v_add_f32_e32 v0, v53, v0
	v_add_f32_e32 v0, v54, v0
	v_add_f32_e32 v0, v55, v0
	v_cvt_pk_bf16_f32 v2, v48, v49
	v_cvt_pk_bf16_f32 v3, v50, v51
	v_cvt_pk_bf16_f32 v4, v52, v53
	v_cvt_pk_bf16_f32 v5, v54, v55
	s_nop 1
	ds_read_b64 v[48:49], v242 offset:20480
	ds_read_b64 v[50:51], v243 offset:20480
	s_waitcnt vmcnt(0) lgkmcnt(0)
	s_mov_b64 s[24:25], exec
	s_mov_b64 exec, 1
	v_mov_b32_e32 v248, s33
	v_mov_b32_e32 v249, 1
	ds_add_u32 v248, v249 offset:8
	s_mov_b64 exec, s[24:25]
	s_waitcnt lgkmcnt(14)
	v_mfma_f32_32x32x16_bf16 v[112:127], v[32:35], v[2:5], v[112:127]
	v_exp_f32_e32 v56, v56
	v_exp_f32_e32 v57, v57
	s_waitcnt lgkmcnt(12)
	v_mfma_f32_32x32x16_bf16 v[64:79], v[40:43], v[2:5], v[64:79]
	v_exp_f32_e32 v58, v58
	v_exp_f32_e32 v59, v59
	v_add_f32_e32 v0, v56, v0
	v_add_f32_e32 v0, v57, v0
	s_waitcnt lgkmcnt(10)
	v_mfma_f32_32x32x16_bf16 v[96:111], v[44:47], v[2:5], v[96:111]
	v_exp_f32_e32 v60, v60
	v_exp_f32_e32 v61, v61
	v_add_f32_e32 v0, v58, v0
	v_add_f32_e32 v0, v59, v0
	s_waitcnt lgkmcnt(8)
	v_mfma_f32_32x32x16_bf16 v[80:95], v[36:39], v[2:5], v[80:95]
	v_exp_f32_e32 v62, v62
	v_exp_f32_e32 v63, v63
	v_add_f32_e32 v0, v60, v0
	v_add_f32_e32 v0, v61, v0
	v_add_f32_e32 v0, v62, v0
	v_add_f32_e32 v0, v63, v0
	v_cvt_pk_bf16_f32 v2, v56, v57
	v_cvt_pk_bf16_f32 v3, v58, v59
	v_cvt_pk_bf16_f32 v4, v60, v61
	v_cvt_pk_bf16_f32 v5, v62, v63
	s_nop 1
	s_waitcnt lgkmcnt(6)
	v_mfma_f32_32x32x16_bf16 v[112:127], v[6:9], v[2:5], v[112:127]
	s_waitcnt lgkmcnt(4)
	v_mfma_f32_32x32x16_bf16 v[96:111], v[10:13], v[2:5], v[96:111]
	s_waitcnt lgkmcnt(2)
	v_mfma_f32_32x32x16_bf16 v[80:95], v[244:247], v[2:5], v[80:95]
	s_waitcnt lgkmcnt(0)
	v_mfma_f32_32x32x16_bf16 v[64:79], v[48:51], v[2:5], v[64:79]
	v_add_f32_e32 v227, v227, v0
	s_branch .LBB0_1376

.LBB0_1381:
	ds_read_b128 v[2:5], v222
	ds_read_b128 v[6:9], v222 offset:4096
	ds_read_b128 v[10:13], v223
	ds_read_b128 v[244:247], v223 offset:4096
	s_waitcnt lgkmcnt(3)
	v_mfma_f32_32x32x16_bf16 v[32:47], v[2:5], v[160:163], v[16:31]
	v_exp_f32_e32 v128, v128
	v_exp_f32_e32 v129, v129
	ds_read_b128 v[2:5], v224
	s_waitcnt lgkmcnt(3)
	v_mfma_f32_32x32x16_bf16 v[48:63], v[6:9], v[160:163], v[16:31]
	v_exp_f32_e32 v130, v130
	v_exp_f32_e32 v131, v131
	ds_read_b128 v[6:9], v224 offset:4096
	s_waitcnt lgkmcnt(3)
	v_mfma_f32_32x32x16_bf16 v[32:47], v[10:13], v[164:167], v[32:47]
	v_exp_f32_e32 v132, v132
	v_exp_f32_e32 v133, v133
	v_add_f32_e32 v0, 0, v128
	ds_read_b128 v[10:13], v225
	s_waitcnt lgkmcnt(3)
	v_mfma_f32_32x32x16_bf16 v[48:63], v[244:247], v[164:167], v[48:63]
	v_exp_f32_e32 v134, v134
	v_exp_f32_e32 v135, v135
	v_add_f32_e32 v0, v129, v0
	ds_read_b128 v[244:247], v225 offset:4096
	s_waitcnt lgkmcnt(3)
	v_mfma_f32_32x32x16_bf16 v[32:47], v[2:5], v[168:171], v[32:47]
	v_cvt_pk_bf16_f32 v208, v128, v129
	v_add_f32_e32 v0, v130, v0
	v_add_f32_e32 v0, v131, v0
	s_waitcnt lgkmcnt(2)
	v_mfma_f32_32x32x16_bf16 v[48:63], v[6:9], v[168:171], v[48:63]
	v_cvt_pk_bf16_f32 v209, v130, v131
	v_add_f32_e32 v0, v132, v0
	v_add_f32_e32 v0, v133, v0
	s_waitcnt lgkmcnt(1)
	v_mfma_f32_32x32x16_bf16 v[32:47], v[10:13], v[172:175], v[32:47]
	v_cvt_pk_bf16_f32 v210, v132, v133
	v_add_f32_e32 v0, v134, v0
	s_waitcnt lgkmcnt(0)
	v_mfma_f32_32x32x16_bf16 v[48:63], v[244:247], v[172:175], v[48:63]
	v_cvt_pk_bf16_f32 v211, v134, v135
	v_add_f32_e32 v0, v135, v0
	s_or_b64 exec, exec, s[20:21]
	s_and_saveexec_b64 s[20:21], s[4:5]
	ds_read_b64 v[6:7], v228 offset:32768
	ds_read_b64 v[8:9], v229 offset:32768
	ds_read_b64 v[10:11], v230 offset:45056
	ds_read_b64 v[12:13], v231 offset:45056
	ds_read_b64 v[244:245], v230 offset:36864
	ds_read_b64 v[246:247], v231 offset:36864
	ds_read_b64 v[128:129], v230 offset:40960
	ds_read_b64 v[130:131], v231 offset:40960
	ds_read_b64 v[132:133], v232 offset:32768
	ds_read_b64 v[134:135], v233 offset:32768
	s_waitcnt lgkmcnt(8)
	v_mfma_f32_32x32x16_bf16 v[112:127], v[6:9], v[208:211], v[112:127]
	ds_read_b64 v[6:7], v234 offset:45056
	ds_read_b64 v[8:9], v235 offset:45056
	v_exp_f32_e32 v136, v136
	v_exp_f32_e32 v137, v137
	s_waitcnt lgkmcnt(8)
	v_mfma_f32_32x32x16_bf16 v[64:79], v[10:13], v[208:211], v[64:79]
	ds_read_b64 v[10:11], v234 offset:36864
	ds_read_b64 v[12:13], v235 offset:36864
	v_exp_f32_e32 v138, v138
	v_exp_f32_e32 v139, v139
	v_add_f32_e32 v0, v136, v0
	v_add_f32_e32 v0, v137, v0
	s_waitcnt lgkmcnt(8)
	v_mfma_f32_32x32x16_bf16 v[96:111], v[244:247], v[208:211], v[96:111]
	ds_read_b64 v[244:245], v234 offset:40960
	ds_read_b64 v[246:247], v235 offset:40960
	v_exp_f32_e32 v140, v140
	v_exp_f32_e32 v141, v141
	v_add_f32_e32 v0, v138, v0
	v_add_f32_e32 v0, v139, v0
	s_waitcnt lgkmcnt(8)
	v_mfma_f32_32x32x16_bf16 v[80:95], v[128:131], v[208:211], v[80:95]
	ds_read_b64 v[128:129], v236 offset:32768
	ds_read_b64 v[130:131], v237 offset:32768
	v_exp_f32_e32 v142, v142
	v_exp_f32_e32 v143, v143
	v_add_f32_e32 v0, v140, v0
	v_add_f32_e32 v0, v141, v0
	v_add_f32_e32 v0, v142, v0
	v_add_f32_e32 v0, v143, v0
	v_cvt_pk_bf16_f32 v2, v136, v137
	v_cvt_pk_bf16_f32 v3, v138, v139
	v_cvt_pk_bf16_f32 v4, v140, v141
	v_cvt_pk_bf16_f32 v5, v142, v143
	s_nop 1
	ds_read_b64 v[136:137], v238 offset:45056
	ds_read_b64 v[138:139], v239 offset:45056
	ds_read_b64 v[140:141], v238 offset:36864
	ds_read_b64 v[142:143], v239 offset:36864
	s_waitcnt lgkmcnt(12)
	v_mfma_f32_32x32x16_bf16 v[112:127], v[132:135], v[2:5], v[112:127]
	ds_read_b64 v[132:133], v238 offset:40960
	ds_read_b64 v[134:135], v239 offset:40960
	v_exp_f32_e32 v144, v144
	v_exp_f32_e32 v145, v145
	s_waitcnt lgkmcnt(12)
	v_mfma_f32_32x32x16_bf16 v[64:79], v[6:9], v[2:5], v[64:79]
	ds_read_b64 v[6:7], v240 offset:32768
	ds_read_b64 v[8:9], v241 offset:32768
	v_exp_f32_e32 v146, v146
	v_exp_f32_e32 v147, v147
	v_add_f32_e32 v0, v144, v0
	v_add_f32_e32 v0, v145, v0
	s_waitcnt lgkmcnt(12)
	v_mfma_f32_32x32x16_bf16 v[96:111], v[10:13], v[2:5], v[96:111]
	ds_read_b64 v[10:11], v242 offset:36864
	ds_read_b64 v[12:13], v243 offset:36864
	v_exp_f32_e32 v148, v148
	v_exp_f32_e32 v149, v149
	v_add_f32_e32 v0, v146, v0
	v_add_f32_e32 v0, v147, v0
	s_waitcnt lgkmcnt(12)
	v_mfma_f32_32x32x16_bf16 v[80:95], v[244:247], v[2:5], v[80:95]
	ds_read_b64 v[244:245], v242 offset:40960
	ds_read_b64 v[246:247], v243 offset:40960
	v_exp_f32_e32 v150, v150
	v_exp_f32_e32 v151, v151
	v_add_f32_e32 v0, v148, v0
	v_add_f32_e32 v0, v149, v0
	v_add_f32_e32 v0, v150, v0
	v_add_f32_e32 v0, v151, v0
	v_cvt_pk_bf16_f32 v2, v144, v145
	v_cvt_pk_bf16_f32 v3, v146, v147
	v_cvt_pk_bf16_f32 v4, v148, v149
	v_cvt_pk_bf16_f32 v5, v150, v151
	s_nop 1
	ds_read_b64 v[144:145], v242 offset:45056
	ds_read_b64 v[146:147], v243 offset:45056
	s_waitcnt vmcnt(0) lgkmcnt(0)
	s_mov_b64 s[24:25], exec
	s_mov_b64 exec, 1
	v_mov_b32_e32 v248, s33
	v_mov_b32_e32 v249, 1
	ds_add_u32 v248, v249 offset:8
	s_mov_b64 exec, s[24:25]
	s_waitcnt lgkmcnt(14)
	v_mfma_f32_32x32x16_bf16 v[112:127], v[128:131], v[2:5], v[112:127]
	v_exp_f32_e32 v152, v152
	v_exp_f32_e32 v153, v153
	s_waitcnt lgkmcnt(12)
	v_mfma_f32_32x32x16_bf16 v[64:79], v[136:139], v[2:5], v[64:79]
	v_exp_f32_e32 v154, v154
	v_exp_f32_e32 v155, v155
	v_add_f32_e32 v0, v152, v0
	v_add_f32_e32 v0, v153, v0
	s_waitcnt lgkmcnt(10)
	v_mfma_f32_32x32x16_bf16 v[96:111], v[140:143], v[2:5], v[96:111]
	v_exp_f32_e32 v156, v156
	v_exp_f32_e32 v157, v157
	v_add_f32_e32 v0, v154, v0
	v_add_f32_e32 v0, v155, v0
	s_waitcnt lgkmcnt(8)
	v_mfma_f32_32x32x16_bf16 v[80:95], v[132:135], v[2:5], v[80:95]
	v_exp_f32_e32 v158, v158
	v_exp_f32_e32 v159, v159
	v_add_f32_e32 v0, v156, v0
	v_add_f32_e32 v0, v157, v0
	v_add_f32_e32 v0, v158, v0
	v_add_f32_e32 v0, v159, v0
	v_cvt_pk_bf16_f32 v2, v152, v153
	v_cvt_pk_bf16_f32 v3, v154, v155
	v_cvt_pk_bf16_f32 v4, v156, v157
	v_cvt_pk_bf16_f32 v5, v158, v159
	s_nop 1
	s_waitcnt lgkmcnt(6)
	v_mfma_f32_32x32x16_bf16 v[112:127], v[6:9], v[2:5], v[112:127]
	s_waitcnt lgkmcnt(4)
	v_mfma_f32_32x32x16_bf16 v[96:111], v[10:13], v[2:5], v[96:111]
	s_waitcnt lgkmcnt(2)
	v_mfma_f32_32x32x16_bf16 v[80:95], v[244:247], v[2:5], v[80:95]
	s_waitcnt lgkmcnt(0)
	v_mfma_f32_32x32x16_bf16 v[64:79], v[144:147], v[2:5], v[64:79]
	v_add_f32_e32 v227, v0, v227
	s_or_b64 exec, exec, s[20:21]
	s_branch .LBB0_1389

.LBB0_1411:
	s_or_b32 s82, s31, 1
	s_lshl_b64 s[4:5], s[82:83], 7
	s_add_u32 s4, s8, s4
	s_addc_u32 s5, s9, s5
	s_add_u32 m0, s38, 0x8000
	s_nop 0
	global_load_lds_dwordx4 v196, s[4:5]
	s_add_u32 m0, s38, 0x9000
	s_nop 0
	global_load_lds_dwordx4 v197, s[4:5]
	s_add_u32 m0, s38, 0xa000
	s_nop 0
	global_load_lds_dwordx4 v198, s[4:5]
	s_add_u32 m0, s38, 0xb000
	s_nop 0
	global_load_lds_dwordx4 v199, s[4:5]
	v_cmp_lt_i32_e64 s[4:5], s31, v225
	s_and_saveexec_b64 s[22:23], s[4:5]
	s_cbranch_execz .LBB0_1413
	ds_read_b128 v[2:5], v220 offset:24576
	ds_read_b128 v[6:9], v220 offset:28672
	ds_read_b128 v[10:13], v221 offset:24576
	ds_read_b128 v[244:247], v221 offset:28672
	s_waitcnt lgkmcnt(3)
	v_mfma_f32_32x32x16_bf16 v[128:143], v[2:5], v[160:163], v[16:31]
	v_exp_f32_e32 v80, v80
	v_exp_f32_e32 v81, v81
	ds_read_b128 v[2:5], v222 offset:24576
	s_waitcnt lgkmcnt(3)
	v_mfma_f32_32x32x16_bf16 v[144:159], v[6:9], v[160:163], v[16:31]
	v_exp_f32_e32 v82, v82
	v_exp_f32_e32 v83, v83
	ds_read_b128 v[6:9], v222 offset:28672
	s_waitcnt lgkmcnt(3)
	v_mfma_f32_32x32x16_bf16 v[128:143], v[10:13], v[164:167], v[128:143]
	v_exp_f32_e32 v84, v84
	v_exp_f32_e32 v85, v85
	v_add_f32_e32 v0, 0, v80
	ds_read_b128 v[10:13], v223 offset:24576
	s_waitcnt lgkmcnt(3)
	v_mfma_f32_32x32x16_bf16 v[144:159], v[244:247], v[164:167], v[144:159]
	v_exp_f32_e32 v86, v86
	v_exp_f32_e32 v87, v87
	v_add_f32_e32 v0, v81, v0
	ds_read_b128 v[244:247], v223 offset:28672
	s_waitcnt lgkmcnt(3)
	v_mfma_f32_32x32x16_bf16 v[128:143], v[2:5], v[168:171], v[128:143]
	v_cvt_pk_bf16_f32 v208, v80, v81
	v_add_f32_e32 v0, v82, v0
	v_add_f32_e32 v0, v83, v0
	s_waitcnt lgkmcnt(2)
	v_mfma_f32_32x32x16_bf16 v[144:159], v[6:9], v[168:171], v[144:159]
	v_cvt_pk_bf16_f32 v209, v82, v83
	v_add_f32_e32 v0, v84, v0
	v_add_f32_e32 v0, v85, v0
	s_waitcnt lgkmcnt(1)
	v_mfma_f32_32x32x16_bf16 v[128:143], v[10:13], v[172:175], v[128:143]
	v_cvt_pk_bf16_f32 v210, v84, v85
	v_add_f32_e32 v0, v86, v0
	s_waitcnt lgkmcnt(0)
	v_mfma_f32_32x32x16_bf16 v[144:159], v[244:247], v[172:175], v[144:159]
	v_cvt_pk_bf16_f32 v211, v86, v87
	v_add_f32_e32 v0, v87, v0
	s_or_b64 exec, exec, s[22:23]
	v_cmp_le_i32_e32 vcc, s31, v225
	s_and_saveexec_b64 s[22:23], vcc
	ds_read_b64 v[6:7], v226 offset:8192
	ds_read_b64 v[8:9], v227 offset:8192
	ds_read_b64 v[10:11], v228 offset:20480
	ds_read_b64 v[12:13], v229 offset:20480
	ds_read_b64 v[242:243], v228 offset:12288
	ds_read_b64 v[244:245], v229 offset:12288
	ds_read_b64 v[80:81], v228 offset:16384
	ds_read_b64 v[82:83], v229 offset:16384
	ds_read_b64 v[84:85], v230 offset:8192
	ds_read_b64 v[86:87], v231 offset:8192
	s_waitcnt lgkmcnt(8)
	v_mfma_f32_32x32x16_bf16 v[64:79], v[6:9], v[208:211], v[64:79]
	ds_read_b64 v[6:7], v232 offset:20480
	ds_read_b64 v[8:9], v233 offset:20480
	v_exp_f32_e32 v88, v88
	v_exp_f32_e32 v89, v89
	s_waitcnt lgkmcnt(8)
	v_mfma_f32_32x32x16_bf16 v[112:127], v[10:13], v[208:211], v[112:127]
	ds_read_b64 v[10:11], v232 offset:12288
	ds_read_b64 v[12:13], v233 offset:12288
	v_exp_f32_e32 v90, v90
	v_exp_f32_e32 v91, v91
	v_add_f32_e32 v0, v88, v0
	v_add_f32_e32 v0, v89, v0
	s_waitcnt lgkmcnt(8)
	v_mfma_f32_32x32x16_bf16 v[48:63], v[242:245], v[208:211], v[48:63]
	ds_read_b64 v[242:243], v232 offset:16384
	ds_read_b64 v[244:245], v233 offset:16384
	v_exp_f32_e32 v92, v92
	v_exp_f32_e32 v93, v93
	v_add_f32_e32 v0, v90, v0
	v_add_f32_e32 v0, v91, v0
	s_waitcnt lgkmcnt(8)
	v_mfma_f32_32x32x16_bf16 v[32:47], v[80:83], v[208:211], v[32:47]
	ds_read_b64 v[80:81], v234 offset:8192
	ds_read_b64 v[82:83], v235 offset:8192
	v_exp_f32_e32 v94, v94
	v_exp_f32_e32 v95, v95
	v_add_f32_e32 v0, v92, v0
	v_add_f32_e32 v0, v93, v0
	v_add_f32_e32 v0, v94, v0
	v_add_f32_e32 v0, v95, v0
	v_cvt_pk_bf16_f32 v2, v88, v89
	v_cvt_pk_bf16_f32 v3, v90, v91
	v_cvt_pk_bf16_f32 v4, v92, v93
	v_cvt_pk_bf16_f32 v5, v94, v95
	s_nop 1
	ds_read_b64 v[88:89], v236 offset:20480
	ds_read_b64 v[90:91], v237 offset:20480
	ds_read_b64 v[92:93], v236 offset:12288
	ds_read_b64 v[94:95], v237 offset:12288
	s_waitcnt lgkmcnt(12)
	v_mfma_f32_32x32x16_bf16 v[64:79], v[84:87], v[2:5], v[64:79]
	ds_read_b64 v[84:85], v236 offset:16384
	ds_read_b64 v[86:87], v237 offset:16384
	v_exp_f32_e32 v96, v96
	v_exp_f32_e32 v97, v97
	s_waitcnt lgkmcnt(12)
	v_mfma_f32_32x32x16_bf16 v[112:127], v[6:9], v[2:5], v[112:127]
	ds_read_b64 v[6:7], v238 offset:8192
	ds_read_b64 v[8:9], v239 offset:8192
	v_exp_f32_e32 v98, v98
	v_exp_f32_e32 v99, v99
	v_add_f32_e32 v0, v96, v0
	v_add_f32_e32 v0, v97, v0
	s_waitcnt lgkmcnt(12)
	v_mfma_f32_32x32x16_bf16 v[48:63], v[10:13], v[2:5], v[48:63]
	ds_read_b64 v[10:11], v240 offset:12288
	ds_read_b64 v[12:13], v241 offset:12288
	v_exp_f32_e32 v100, v100
	v_exp_f32_e32 v101, v101
	v_add_f32_e32 v0, v98, v0
	v_add_f32_e32 v0, v99, v0
	s_waitcnt lgkmcnt(12)
	v_mfma_f32_32x32x16_bf16 v[32:47], v[242:245], v[2:5], v[32:47]
	ds_read_b64 v[242:243], v240 offset:16384
	ds_read_b64 v[244:245], v241 offset:16384
	v_exp_f32_e32 v102, v102
	v_exp_f32_e32 v103, v103
	v_add_f32_e32 v0, v100, v0
	v_add_f32_e32 v0, v101, v0
	v_add_f32_e32 v0, v102, v0
	v_add_f32_e32 v0, v103, v0
	v_cvt_pk_bf16_f32 v2, v96, v97
	v_cvt_pk_bf16_f32 v3, v98, v99
	v_cvt_pk_bf16_f32 v4, v100, v101
	v_cvt_pk_bf16_f32 v5, v102, v103
	s_nop 1
	ds_read_b64 v[96:97], v240 offset:20480
	ds_read_b64 v[98:99], v241 offset:20480
	s_waitcnt vmcnt(0) lgkmcnt(0)
	s_mov_b64 s[24:25], exec
	s_mov_b64 exec, 1
	v_mov_b32_e32 v248, s33
	v_mov_b32_e32 v249, 1
	ds_add_u32 v248, v249 offset:8
	s_mov_b64 exec, s[24:25]
	s_waitcnt lgkmcnt(14)
	v_mfma_f32_32x32x16_bf16 v[64:79], v[80:83], v[2:5], v[64:79]
	v_exp_f32_e32 v104, v104
	v_exp_f32_e32 v105, v105
	s_waitcnt lgkmcnt(12)
	v_mfma_f32_32x32x16_bf16 v[112:127], v[88:91], v[2:5], v[112:127]
	v_exp_f32_e32 v106, v106
	v_exp_f32_e32 v107, v107
	v_add_f32_e32 v0, v104, v0
	v_add_f32_e32 v0, v105, v0
	s_waitcnt lgkmcnt(10)
	v_mfma_f32_32x32x16_bf16 v[48:63], v[92:95], v[2:5], v[48:63]
	v_exp_f32_e32 v108, v108
	v_exp_f32_e32 v109, v109
	v_add_f32_e32 v0, v106, v0
	v_add_f32_e32 v0, v107, v0
	s_waitcnt lgkmcnt(8)
	v_mfma_f32_32x32x16_bf16 v[32:47], v[84:87], v[2:5], v[32:47]
	v_exp_f32_e32 v110, v110
	v_exp_f32_e32 v111, v111
	v_add_f32_e32 v0, v108, v0
	v_add_f32_e32 v0, v109, v0
	v_add_f32_e32 v0, v110, v0
	v_add_f32_e32 v0, v111, v0
	v_cvt_pk_bf16_f32 v2, v104, v105
	v_cvt_pk_bf16_f32 v3, v106, v107
	v_cvt_pk_bf16_f32 v4, v108, v109
	v_cvt_pk_bf16_f32 v5, v110, v111
	s_nop 1
	s_waitcnt lgkmcnt(6)
	v_mfma_f32_32x32x16_bf16 v[64:79], v[6:9], v[2:5], v[64:79]
	s_waitcnt lgkmcnt(4)
	v_mfma_f32_32x32x16_bf16 v[48:63], v[10:13], v[2:5], v[48:63]
	s_waitcnt lgkmcnt(2)
	v_mfma_f32_32x32x16_bf16 v[32:47], v[242:245], v[2:5], v[32:47]
	s_waitcnt lgkmcnt(0)
	v_mfma_f32_32x32x16_bf16 v[112:127], v[96:99], v[2:5], v[112:127]
	v_add_f32_e32 v224, v224, v0
	s_branch .LBB0_1418

.LBB0_1423:
	ds_read_b128 v[2:5], v220
	ds_read_b128 v[6:9], v220 offset:4096
	ds_read_b128 v[10:13], v221
	ds_read_b128 v[244:247], v221 offset:4096
	s_waitcnt lgkmcnt(3)
	v_mfma_f32_32x32x16_bf16 v[80:95], v[2:5], v[160:163], v[16:31]
	v_exp_f32_e32 v128, v128
	v_exp_f32_e32 v129, v129
	ds_read_b128 v[2:5], v222
	s_waitcnt lgkmcnt(3)
	v_mfma_f32_32x32x16_bf16 v[96:111], v[6:9], v[160:163], v[16:31]
	v_exp_f32_e32 v130, v130
	v_exp_f32_e32 v131, v131
	ds_read_b128 v[6:9], v222 offset:4096
	s_waitcnt lgkmcnt(3)
	v_mfma_f32_32x32x16_bf16 v[80:95], v[10:13], v[164:167], v[80:95]
	v_exp_f32_e32 v132, v132
	v_exp_f32_e32 v133, v133
	v_add_f32_e32 v0, 0, v128
	ds_read_b128 v[10:13], v223
	s_waitcnt lgkmcnt(3)
	v_mfma_f32_32x32x16_bf16 v[96:111], v[244:247], v[164:167], v[96:111]
	v_exp_f32_e32 v134, v134
	v_exp_f32_e32 v135, v135
	v_add_f32_e32 v0, v129, v0
	ds_read_b128 v[244:247], v223 offset:4096
	s_waitcnt lgkmcnt(3)
	v_mfma_f32_32x32x16_bf16 v[80:95], v[2:5], v[168:171], v[80:95]
	v_cvt_pk_bf16_f32 v208, v128, v129
	v_add_f32_e32 v0, v130, v0
	v_add_f32_e32 v0, v131, v0
	s_waitcnt lgkmcnt(2)
	v_mfma_f32_32x32x16_bf16 v[96:111], v[6:9], v[168:171], v[96:111]
	v_cvt_pk_bf16_f32 v209, v130, v131
	v_add_f32_e32 v0, v132, v0
	v_add_f32_e32 v0, v133, v0
	s_waitcnt lgkmcnt(1)
	v_mfma_f32_32x32x16_bf16 v[80:95], v[10:13], v[172:175], v[80:95]
	v_cvt_pk_bf16_f32 v210, v132, v133
	v_add_f32_e32 v0, v134, v0
	s_waitcnt lgkmcnt(0)
	v_mfma_f32_32x32x16_bf16 v[96:111], v[244:247], v[172:175], v[96:111]
	v_cvt_pk_bf16_f32 v211, v134, v135
	v_add_f32_e32 v0, v135, v0
	s_or_b64 exec, exec, s[20:21]
	s_and_saveexec_b64 s[20:21], s[4:5]
	ds_read_b64 v[6:7], v226 offset:32768
	ds_read_b64 v[8:9], v227 offset:32768
	ds_read_b64 v[10:11], v228 offset:45056
	ds_read_b64 v[12:13], v229 offset:45056
	ds_read_b64 v[242:243], v228 offset:36864
	ds_read_b64 v[244:245], v229 offset:36864
	ds_read_b64 v[128:129], v228 offset:40960
	ds_read_b64 v[130:131], v229 offset:40960
	ds_read_b64 v[132:133], v230 offset:32768
	ds_read_b64 v[134:135], v231 offset:32768
	s_waitcnt lgkmcnt(8)
	v_mfma_f32_32x32x16_bf16 v[64:79], v[6:9], v[208:211], v[64:79]
	ds_read_b64 v[6:7], v232 offset:45056
	ds_read_b64 v[8:9], v233 offset:45056
	v_exp_f32_e32 v136, v136
	v_exp_f32_e32 v137, v137
	s_waitcnt lgkmcnt(8)
	v_mfma_f32_32x32x16_bf16 v[112:127], v[10:13], v[208:211], v[112:127]
	ds_read_b64 v[10:11], v232 offset:36864
	ds_read_b64 v[12:13], v233 offset:36864
	v_exp_f32_e32 v138, v138
	v_exp_f32_e32 v139, v139
	v_add_f32_e32 v0, v136, v0
	v_add_f32_e32 v0, v137, v0
	s_waitcnt lgkmcnt(8)
	v_mfma_f32_32x32x16_bf16 v[48:63], v[242:245], v[208:211], v[48:63]
	ds_read_b64 v[242:243], v232 offset:40960
	ds_read_b64 v[244:245], v233 offset:40960
	v_exp_f32_e32 v140, v140
	v_exp_f32_e32 v141, v141
	v_add_f32_e32 v0, v138, v0
	v_add_f32_e32 v0, v139, v0
	s_waitcnt lgkmcnt(8)
	v_mfma_f32_32x32x16_bf16 v[32:47], v[128:131], v[208:211], v[32:47]
	ds_read_b64 v[128:129], v234 offset:32768
	ds_read_b64 v[130:131], v235 offset:32768
	v_exp_f32_e32 v142, v142
	v_exp_f32_e32 v143, v143
	v_add_f32_e32 v0, v140, v0
	v_add_f32_e32 v0, v141, v0
	v_add_f32_e32 v0, v142, v0
	v_add_f32_e32 v0, v143, v0
	v_cvt_pk_bf16_f32 v2, v136, v137
	v_cvt_pk_bf16_f32 v3, v138, v139
	v_cvt_pk_bf16_f32 v4, v140, v141
	v_cvt_pk_bf16_f32 v5, v142, v143
	s_nop 1
	ds_read_b64 v[136:137], v236 offset:45056
	ds_read_b64 v[138:139], v237 offset:45056
	ds_read_b64 v[140:141], v236 offset:36864
	ds_read_b64 v[142:143], v237 offset:36864
	s_waitcnt lgkmcnt(12)
	v_mfma_f32_32x32x16_bf16 v[64:79], v[132:135], v[2:5], v[64:79]
	ds_read_b64 v[132:133], v236 offset:40960
	ds_read_b64 v[134:135], v237 offset:40960
	v_exp_f32_e32 v144, v144
	v_exp_f32_e32 v145, v145
	s_waitcnt lgkmcnt(12)
	v_mfma_f32_32x32x16_bf16 v[112:127], v[6:9], v[2:5], v[112:127]
	ds_read_b64 v[6:7], v238 offset:32768
	ds_read_b64 v[8:9], v239 offset:32768
	v_exp_f32_e32 v146, v146
	v_exp_f32_e32 v147, v147
	v_add_f32_e32 v0, v144, v0
	v_add_f32_e32 v0, v145, v0
	s_waitcnt lgkmcnt(12)
	v_mfma_f32_32x32x16_bf16 v[48:63], v[10:13], v[2:5], v[48:63]
	ds_read_b64 v[10:11], v240 offset:36864
	ds_read_b64 v[12:13], v241 offset:36864
	v_exp_f32_e32 v148, v148
	v_exp_f32_e32 v149, v149
	v_add_f32_e32 v0, v146, v0
	v_add_f32_e32 v0, v147, v0
	s_waitcnt lgkmcnt(12)
	v_mfma_f32_32x32x16_bf16 v[32:47], v[242:245], v[2:5], v[32:47]
	ds_read_b64 v[242:243], v240 offset:40960
	ds_read_b64 v[244:245], v241 offset:40960
	v_exp_f32_e32 v150, v150
	v_exp_f32_e32 v151, v151
	v_add_f32_e32 v0, v148, v0
	v_add_f32_e32 v0, v149, v0
	v_add_f32_e32 v0, v150, v0
	v_add_f32_e32 v0, v151, v0
	v_cvt_pk_bf16_f32 v2, v144, v145
	v_cvt_pk_bf16_f32 v3, v146, v147
	v_cvt_pk_bf16_f32 v4, v148, v149
	v_cvt_pk_bf16_f32 v5, v150, v151
	s_nop 1
	ds_read_b64 v[144:145], v240 offset:45056
	ds_read_b64 v[146:147], v241 offset:45056
	s_waitcnt vmcnt(0) lgkmcnt(0)
	s_mov_b64 s[24:25], exec
	s_mov_b64 exec, 1
	v_mov_b32_e32 v248, s33
	v_mov_b32_e32 v249, 1
	ds_add_u32 v248, v249 offset:8
	s_mov_b64 exec, s[24:25]
	s_waitcnt lgkmcnt(14)
	v_mfma_f32_32x32x16_bf16 v[64:79], v[128:131], v[2:5], v[64:79]
	v_exp_f32_e32 v152, v152
	v_exp_f32_e32 v153, v153
	s_waitcnt lgkmcnt(12)
	v_mfma_f32_32x32x16_bf16 v[112:127], v[136:139], v[2:5], v[112:127]
	v_exp_f32_e32 v154, v154
	v_exp_f32_e32 v155, v155
	v_add_f32_e32 v0, v152, v0
	v_add_f32_e32 v0, v153, v0
	s_waitcnt lgkmcnt(10)
	v_mfma_f32_32x32x16_bf16 v[48:63], v[140:143], v[2:5], v[48:63]
	v_exp_f32_e32 v156, v156
	v_exp_f32_e32 v157, v157
	v_add_f32_e32 v0, v154, v0
	v_add_f32_e32 v0, v155, v0
	s_waitcnt lgkmcnt(8)
	v_mfma_f32_32x32x16_bf16 v[32:47], v[132:135], v[2:5], v[32:47]
	v_exp_f32_e32 v158, v158
	v_exp_f32_e32 v159, v159
	v_add_f32_e32 v0, v156, v0
	v_add_f32_e32 v0, v157, v0
	v_add_f32_e32 v0, v158, v0
	v_add_f32_e32 v0, v159, v0
	v_cvt_pk_bf16_f32 v2, v152, v153
	v_cvt_pk_bf16_f32 v3, v154, v155
	v_cvt_pk_bf16_f32 v4, v156, v157
	v_cvt_pk_bf16_f32 v5, v158, v159
	s_nop 1
	s_waitcnt lgkmcnt(6)
	v_mfma_f32_32x32x16_bf16 v[64:79], v[6:9], v[2:5], v[64:79]
	s_waitcnt lgkmcnt(4)
	v_mfma_f32_32x32x16_bf16 v[48:63], v[10:13], v[2:5], v[48:63]
	s_waitcnt lgkmcnt(2)
	v_mfma_f32_32x32x16_bf16 v[32:47], v[242:245], v[2:5], v[32:47]
	s_waitcnt lgkmcnt(0)
	v_mfma_f32_32x32x16_bf16 v[112:127], v[144:147], v[2:5], v[112:127]
	v_add_f32_e32 v224, v0, v224
	s_or_b64 exec, exec, s[20:21]
	s_branch .LBB0_1431
